# v28 + one Q fragment kept resident in the spare VGPRs v[250:253] for the whole K-loop (2 fewer ds_read_b128 per iteration)
# speedup vs baseline: 1.0066x; 1.0066x over previous
; #define DMA_K(t, bf) do { if (ABL & 8) break; const char* kb_ = Kt + (size_t)(t) * KSTEP; LAS unsigned char* kd_ = Kl + (bf) * SHM_K + wid * 1024; \
;     glds16(kb_ + voffK, kd_); glds16(kb_ + 128 + voffK, kd_ + 8192); glds16(Pt + (size_t)(t) * PSTEP + voffP, kd_ + 16384); } while (0)
; #define DMA_V(t, bf) do { if (ABL & 8) break; const char* vb_ = Kt + 256 + (size_t)(t) * KSTEP; LAS unsigned char* vd_ = Vl + (bf) * SHM_V + wid * 1024; \
;     glds16(vb_ + voffV, vd_); glds16(vb_ + (size_t)32 * LDKV * 2 + voffV, vd_ + 8192); } while (0)
; #define END_STEP() do { if (!(ABL & 8)) { asm volatile("s_waitcnt vmcnt(0)" ::: "memory"); __syncthreads(); } } while (0)
; #define RESC(a) do { if (__any((a) < 1.f)) { if (hi == 0) al_l[r32] = (a); asm volatile("s_waitcnt lgkmcnt(0)" ::: "memory"); \
;     _Pragma("unroll") for (int d = 0; d < 4; ++d) _Pragma("unroll") for (int r = 0; r < 16; ++r) o[d][r] *= al_l[crow(r, hi)]; } } while (0)
; template <int ABL> __device__ __forceinline__ void attn_unit(int b, int h, int qb, const bf16_t* Q, const bf16_t* KV, const bf16_t* KPE, bf16_t* MG, float* ssqa, LAS unsigned char* L) {
;     ...
;   END_STEP();
;   QK_TILE(Kl, pA0, pA1, pA0, pA1, 1.f, false); PAR_ONLY(pA0, pA1, alA);
;   RESC(alA);
;   END_STEP(); DMA_K(2, 0); DMA_V(1, 1);
;   for (int j = 1; j + 1 < NT; j += 2) {
.LBB0_753:
	s_mov_b32 m0, s59
	v_sub_f32_e32 v1, v36, v140
	v_sub_f32_e32 v2, v37, v140
	v_lshl_add_u64 v[36:37], v[52:53], 0, s[8:9]
	s_mov_b64 s[0:1], 0x80080
	s_waitcnt vmcnt(0)
	s_barrier
	global_load_lds_dwordx4 v[36:37], off
	v_lshl_add_u64 v[36:37], v[52:53], 0, s[0:1]
	s_mov_b32 m0, s60
	s_mov_b64 s[0:1], 0x40100
	global_load_lds_dwordx4 v[36:37], off
	v_lshl_add_u64 v[36:37], v[54:55], 0, s[10:11]
	s_mov_b32 m0, s61
	s_add_i32 s79, s58, 0x4000
	global_load_lds_dwordx4 v[36:37], off
	v_lshl_add_u64 v[36:37], v[142:143], 0, s[0:1]
	s_mov_b32 m0, s79
	s_mov_b64 s[0:1], 0x60100
	s_add_i32 s80, s58, 0x6000
	global_load_lds_dwordx4 v[36:37], off
	v_lshl_add_u64 v[36:37], v[142:143], 0, s[0:1]
	s_mov_b32 m0, s80
	v_exp_f32_e32 v68, v1
	global_load_lds_dwordx4 v[36:37], off
	v_exp_f32_e32 v1, v2
	v_lshlrev_b32_e32 v2, 3, v56
	v_sub_f32_e32 v130, v20, v140
	v_sub_f32_e32 v131, v21, v140
	v_sub_f32_e32 v132, v22, v140
	v_and_b32_e32 v20, 24, v2
	v_and_b32_e32 v21, 0xc0, v62
	v_lshlrev_b32_e32 v22, 1, v56
	s_lshr_b32 s54, s2, 4
	v_and_b32_e32 v22, 32, v22
	v_and_b32_e32 v2, 0x100, v2
	v_add3_u32 v20, 0, v20, v21
	s_and_b32 s0, s54, 7
	v_add3_u32 v167, v20, v22, v2
	v_lshlrev_b32_e32 v2, 7, v57
	s_lshl_b32 s54, s0, 9
	s_add_i32 s0, 0, 0x10000
	v_add3_u32 v2, s86, v2, v58
	v_add_u32_e32 v181, s0, v63
	s_add_i32 s0, 0, 0x12000
	v_lshl_add_u64 v[144:145], s[74:75], 0, v[2:3]
	v_lshlrev_b32_e32 v2, 12, v57
	s_add_u32 s54, s72, s54
	v_lshl_add_u32 v2, s83, 15, v2
	s_addc_u32 s55, s73, 0
	v_or_b32_e32 v2, v2, v58
	s_add_i32 s85, s85, s84
	s_lshl_b32 s72, s82, 1
	v_sub_f32_e32 v38, v38, v140
	v_sub_f32_e32 v39, v39, v140
	v_sub_f32_e32 v40, v40, v140
	v_sub_f32_e32 v41, v41, v140
	v_sub_f32_e32 v42, v42, v140
	v_sub_f32_e32 v43, v43, v140
	v_sub_f32_e32 v44, v44, v140
	v_sub_f32_e32 v36, v45, v140
	v_sub_f32_e32 v37, v46, v140
	v_sub_f32_e32 v45, v47, v140
	v_sub_f32_e32 v46, v48, v140
	v_sub_f32_e32 v47, v49, v140
	v_sub_f32_e32 v48, v50, v140
	v_sub_f32_e32 v49, v51, v140
	v_lshl_add_u64 v[146:147], s[54:55], 0, v[2:3]
	v_add3_u32 v2, s85, v59, v60
	s_and_b32 s72, s72, 0x80
	v_exp_f32_e32 v112, v38
	v_exp_f32_e32 v113, v39
	v_exp_f32_e32 v110, v40
	v_exp_f32_e32 v111, v41
	v_exp_f32_e32 v108, v42
	v_exp_f32_e32 v109, v43
	v_exp_f32_e32 v106, v44
	v_exp_f32_e32 v107, v36
	v_exp_f32_e32 v104, v37
	v_lshl_or_b32 v2, v2, 12, s72
	v_exp_f32_e32 v105, v45
	v_exp_f32_e32 v102, v46
	v_exp_f32_e32 v103, v47
	v_exp_f32_e32 v100, v48
	v_exp_f32_e32 v101, v49
	v_lshl_add_u32 v2, v164, 6, v2
	v_sub_f32_e32 v133, v23, v140
	v_sub_f32_e32 v160, v24, v140
	v_sub_f32_e32 v161, v25, v140
	v_sub_f32_e32 v158, v26, v140
	v_sub_f32_e32 v159, v27, v140
	v_sub_f32_e32 v156, v28, v140
	v_sub_f32_e32 v157, v29, v140
	v_sub_f32_e32 v154, v30, v140
	v_sub_f32_e32 v155, v31, v140
	v_sub_f32_e32 v152, v32, v140
	v_sub_f32_e32 v153, v33, v140
	v_sub_f32_e32 v150, v34, v140
	v_sub_f32_e32 v151, v35, v140
	v_add_u32_e32 v182, s34, v63
	v_add_u32_e32 v183, s0, v63
	v_add_u32_e32 v184, s53, v63
	v_cmp_gt_u32_e64 s[0:1], 32, v56
	v_or_b32_e32 v2, v2, v61
	v_mov_b64_e32 v[66:67], v[18:19]
	v_mov_b64_e32 v[50:51], v[18:19]
	v_mov_b64_e32 v[34:35], v[18:19]
	s_mov_b32 s81, 1
	v_lshl_add_u32 v166, v163, 2, s57
	v_lshl_add_u64 v[148:149], s[54:55], 0, v[2:3]
	v_mov_b32_e32 v2, 0
	v_mov_b64_e32 v[64:65], v[16:17]
	v_mov_b64_e32 v[62:63], v[14:15]
	v_mov_b64_e32 v[60:61], v[12:13]
	v_mov_b64_e32 v[58:59], v[10:11]
	v_mov_b64_e32 v[56:57], v[8:9]
	v_mov_b64_e32 v[54:55], v[6:7]
	v_mov_b64_e32 v[52:53], v[4:5]
	v_mov_b64_e32 v[48:49], v[16:17]
	v_mov_b64_e32 v[46:47], v[14:15]
	v_mov_b64_e32 v[44:45], v[12:13]
	v_mov_b64_e32 v[42:43], v[10:11]
	v_mov_b64_e32 v[40:41], v[8:9]
	v_mov_b64_e32 v[38:39], v[6:7]
	v_mov_b64_e32 v[36:37], v[4:5]
	v_mov_b64_e32 v[32:33], v[16:17]
	v_mov_b64_e32 v[30:31], v[14:15]
	v_mov_b64_e32 v[28:29], v[12:13]
	v_mov_b64_e32 v[26:27], v[10:11]
	v_mov_b64_e32 v[24:25], v[8:9]
	v_mov_b64_e32 v[22:23], v[6:7]
	v_mov_b64_e32 v[20:21], v[4:5]
	ds_read_b128 v[250:253], v171
	s_waitcnt lgkmcnt(0)
; template <int G> __device__ __forceinline__ void fin_gap(f32x16& P0, f32x16& P1, float (&sacc)[4], unsigned (&cv)[16], u32x4 (&pw)[4]) {
;   if constexpr (G < 16) { P1[G] = __builtin_amdgcn_exp2f(P1[G]); sacc[G & 3] += P0[G]; }
;   else { constexpr int r = 2 * (G - 16); sacc[r & 3] += P1[r]; sacc[(r + 1) & 3] += P1[r + 1]; }
;   if constexpr (G < 4) cv[G] = cvtpk_c(P0[2 * G], P0[2 * G + 1]);
;   else if constexpr (G >= 6 && G < 10) { constexpr int i = G - 2; cv[i] = cvtpk_c(P0[2 * i], P0[2 * i + 1]); }
;   else if constexpr (G >= 12 && G < 16) { constexpr int i = G - 4, j = i - 8; cv[i] = cvtpk_c(P1[2 * j], P1[2 * j + 1]); }
;   else if constexpr (G >= 18 && G < 22) { constexpr int i = G - 6, j = i - 8; cv[i] = cvtpk_c(P1[2 * j], P1[2 * j + 1]); }
;   if constexpr (G == 4 || G == 10 || G == 16 || G == 22) { constexpr int q = (G - 4) / 6; auto r0 = __builtin_amdgcn_permlane32_swap(cv[4 * q], cv[4 * q + 2], false, false); pw[q].x = r0[0]; pw[q].z = r0[1]; }
;   if constexpr (G == 5 || G == 11 || G == 17 || G == 23) { constexpr int q = (G - 5) / 6; auto r1 = __builtin_amdgcn_permlane32_swap(cv[4 * q + 1], cv[4 * q + 3], false, false); pw[q].y = r1[0]; pw[q].w = r1[1]; }
; }
.LBB0_754:
	ds_read_b128 v[70:73], v178 offset:57344
	ds_read_b128 v[74:77], v178 offset:61440
	s_waitcnt lgkmcnt(0)
	ds_read_b128 v[134:137], v179 offset:57344
	ds_read_b128 v[186:189], v179 offset:61440
	v_mfma_f32_32x32x16_bf16 v[84:99], v[70:73], v[126:129], 0
	v_exp_f32_e32 v210, v130
	v_add_f32_e32 v185, 0, v68
	v_cvt_pk_bf16_f32 v130, v68, v1
	v_mfma_f32_32x32x16_bf16 v[68:83], v[74:77], v[126:129], 0
	v_exp_f32_e32 v211, v131
	v_add_f32_e32 v1, 0, v1
	v_cvt_pk_bf16_f32 v131, v112, v113
	s_waitcnt lgkmcnt(0)
	ds_read_b128 v[190:193], v177 offset:57344
	ds_read_b128 v[194:197], v177 offset:61440
	v_mfma_f32_32x32x16_bf16 v[84:99], v[134:137], v[122:125], v[84:99]
	v_exp_f32_e32 v212, v132
	v_add_f32_e32 v202, 0, v112
	v_cvt_pk_bf16_f32 v132, v110, v111
	v_mfma_f32_32x32x16_bf16 v[68:83], v[186:189], v[122:125], v[68:83]
	v_exp_f32_e32 v213, v133
	v_add_f32_e32 v203, 0, v113
	v_cvt_pk_bf16_f32 v133, v108, v109
	s_waitcnt lgkmcnt(0)
	ds_read_b128 v[134:137], v176 offset:57344
	ds_read_b128 v[198:201], v176 offset:61440
	v_mfma_f32_32x32x16_bf16 v[84:99], v[190:193], v[118:121], v[84:99]
	v_add_f32_e32 v189, v110, v185
	v_permlane32_swap_b32_e32 v130, v132
	v_exp_f32_e32 v214, v160
	v_mfma_f32_32x32x16_bf16 v[68:83], v[194:197], v[118:121], v[68:83]
	v_add_f32_e32 v1, v111, v1
	v_permlane32_swap_b32_e32 v131, v133
	v_exp_f32_e32 v215, v161
	s_waitcnt lgkmcnt(0)
	v_add_u32_e32 v185, v181, v172
	v_add_u32_e32 v186, v182, v172
	ds_read_b128 v[110:113], v185
	ds_read_b128 v[190:193], v186
	v_mfma_f32_32x32x16_bf16 v[84:99], v[134:137], v[114:117], v[84:99]
	v_add_f32_e32 v217, v108, v202
	v_cvt_pk_bf16_f32 v108, v106, v107
	v_exp_f32_e32 v216, v158
	v_mfma_f32_32x32x16_bf16 v[68:83], v[198:201], v[114:117], v[68:83]
	v_add_f32_e32 v219, v109, v203
	v_cvt_pk_bf16_f32 v109, v104, v105
	v_exp_f32_e32 v218, v159
	s_waitcnt lgkmcnt(0)
	v_add_u32_e32 v187, v181, v173
	v_add_u32_e32 v188, v182, v173
	ds_read_b128 v[134:137], v187
	ds_read_b128 v[158:161], v188
	ds_read_b128 v[198:201], v170
	v_mfma_f32_32x32x16_bf16 v[84:99], v[110:113], v[250:253], v[84:99]
	v_cvt_pk_bf16_f32 v110, v102, v103
	v_exp_f32_e32 v220, v156
	v_add_f32_e32 v112, v106, v189
	v_mfma_f32_32x32x16_bf16 v[68:83], v[190:193], v[250:253], v[68:83]
	v_add_f32_e32 v1, v107, v1
	v_cvt_pk_bf16_f32 v111, v100, v101
	v_exp_f32_e32 v113, v157
	s_waitcnt lgkmcnt(0)
	v_add_u32_e32 v189, v181, v174
	v_add_u32_e32 v190, v182, v174
	ds_read_b128 v[194:197], v189
	ds_read_b128 v[202:205], v190
	ds_read_b128 v[206:209], v169
	v_mfma_f32_32x32x16_bf16 v[84:99], v[134:137], v[198:201], v[84:99]
	v_permlane32_swap_b32_e32 v108, v110
	v_exp_f32_e32 v221, v154
	v_add_f32_e32 v217, v104, v217
	v_mfma_f32_32x32x16_bf16 v[68:83], v[158:161], v[198:201], v[68:83]
	v_permlane32_swap_b32_e32 v109, v111
	v_exp_f32_e32 v222, v155
	v_add_f32_e32 v219, v105, v219
	s_waitcnt lgkmcnt(0)
	v_add_u32_e32 v191, v181, v175
	v_add_u32_e32 v192, v182, v175
	ds_read_b128 v[104:107], v191
	ds_read_b128 v[134:137], v192
	ds_read_b128 v[154:157], v168
	v_mfma_f32_32x32x16_bf16 v[84:99], v[194:197], v[206:209], v[84:99]
	v_add_f32_e32 v112, v102, v112
	v_cvt_pk_bf16_f32 v102, v210, v211
	v_exp_f32_e32 v223, v152
	v_mfma_f32_32x32x16_bf16 v[68:83], v[202:205], v[206:209], v[68:83]
	v_add_f32_e32 v1, v103, v1
	v_cvt_pk_bf16_f32 v103, v212, v213
	v_exp_f32_e32 v226, v153
	s_waitcnt lgkmcnt(0)
	v_add_u32_e32 v193, v183, v172
	v_add_u32_e32 v194, v184, v172
	ds_read_b128 v[158:161], v193
	ds_read_b128 v[198:201], v194
	ds_read_b128 v[202:205], v171 offset:4096
	v_mfma_f32_32x32x16_bf16 v[84:99], v[104:107], v[154:157], v[84:99]
	v_cvt_pk_bf16_f32 v104, v214, v215
	v_exp_f32_e32 v227, v150
	v_add_f32_e32 v100, v100, v217
	v_mfma_f32_32x32x16_bf16 v[68:83], v[134:137], v[154:157], v[68:83]
	v_cvt_pk_bf16_f32 v105, v216, v218
	v_exp_f32_e32 v106, v151
	v_add_f32_e32 v101, v101, v219
	s_waitcnt lgkmcnt(0)
	v_add_u32_e32 v195, v183, v173
	v_add_u32_e32 v196, v184, v173
	ds_read_b128 v[134:137], v195
	ds_read_b128 v[150:153], v196
	ds_read_b128 v[154:157], v170 offset:4096
	v_mfma_f32_32x32x16_bf16 v[84:99], v[158:161], v[202:205], v[84:99]
	v_add_f32_e32 v1, v211, v1
	v_permlane32_swap_b32_e32 v102, v104
	v_add_f32_e32 v107, v210, v112
	v_mfma_f32_32x32x16_bf16 v[68:83], v[198:201], v[202:205], v[68:83]
	v_permlane32_swap_b32_e32 v103, v105
	v_add_f32_e32 v100, v212, v100
	v_add_f32_e32 v101, v213, v101
	s_waitcnt lgkmcnt(0)
	v_add_u32_e32 v197, v183, v174
	v_add_u32_e32 v198, v184, v174
	ds_read_b128 v[158:161], v197
	ds_read_b128 v[202:205], v198
	ds_read_b128 v[206:209], v169 offset:4096
	v_mfma_f32_32x32x16_bf16 v[84:99], v[134:137], v[154:157], v[84:99]
	v_add_f32_e32 v1, v215, v1
	v_cvt_pk_bf16_f32 v134, v220, v113
	v_add_f32_e32 v107, v214, v107
	v_mfma_f32_32x32x16_bf16 v[68:83], v[150:153], v[154:157], v[68:83]
	v_cvt_pk_bf16_f32 v135, v221, v222
	v_add_f32_e32 v100, v216, v100
	v_add_f32_e32 v101, v218, v101
	s_waitcnt lgkmcnt(0)
	v_add_u32_e32 v199, v183, v175
	v_add_u32_e32 v200, v184, v175
	ds_read_b128 v[150:153], v199
	ds_read_b128 v[154:157], v200
	ds_read_b128 v[210:213], v168 offset:4096
	v_mfma_f32_32x32x16_bf16 v[84:99], v[158:161], v[206:209], v[84:99]
	v_add_f32_e32 v1, v113, v1
	v_cvt_pk_bf16_f32 v136, v223, v226
	v_add_f32_e32 v107, v220, v107
	v_mfma_f32_32x32x16_bf16 v[68:83], v[202:205], v[206:209], v[68:83]
	v_cvt_pk_bf16_f32 v137, v227, v106
	v_add_f32_e32 v100, v221, v100
	v_add_f32_e32 v101, v222, v101
	s_waitcnt lgkmcnt(0)
	v_mfma_f32_32x32x16_bf16 v[84:99], v[150:153], v[210:213], v[84:99]
	v_add_f32_e32 v1, v226, v1
	v_permlane32_swap_b32_e32 v134, v136
	v_add_f32_e32 v107, v223, v107
	v_mfma_f32_32x32x16_bf16 v[68:83], v[154:157], v[210:213], v[68:83]
	v_permlane32_swap_b32_e32 v135, v137
	v_add_f32_e32 v100, v227, v100
	v_add_f32_e32 v101, v106, v101
	v_add_f32_e32 v1, v107, v1
	v_add_f32_e32 v100, v100, v101
	v_add_f32_e32 v201, v1, v100
	v_mov_b32_e32 v202, v201
	s_nop 1
	v_permlane32_swap_b32_e32 v201, v202

; template <int G> __device__ __forceinline__ void fin_gap(f32x16& P0, f32x16& P1, float (&sacc)[4], unsigned (&cv)[16], u32x4 (&pw)[4]) {
;   if constexpr (G < 16) { P1[G] = __builtin_amdgcn_exp2f(P1[G]); sacc[G & 3] += P0[G]; }
;   else { constexpr int r = 2 * (G - 16); sacc[r & 3] += P1[r]; sacc[(r + 1) & 3] += P1[r + 1]; }
;   if constexpr (G < 4) cv[G] = cvtpk_c(P0[2 * G], P0[2 * G + 1]);
;   else if constexpr (G >= 6 && G < 10) { constexpr int i = G - 2; cv[i] = cvtpk_c(P0[2 * i], P0[2 * i + 1]); }
;   else if constexpr (G >= 12 && G < 16) { constexpr int i = G - 4, j = i - 8; cv[i] = cvtpk_c(P1[2 * j], P1[2 * j + 1]); }
;   else if constexpr (G >= 18 && G < 22) { constexpr int i = G - 6, j = i - 8; cv[i] = cvtpk_c(P1[2 * j], P1[2 * j + 1]); }
;   if constexpr (G == 4 || G == 10 || G == 16 || G == 22) { constexpr int q = (G - 4) / 6; auto r0 = __builtin_amdgcn_permlane32_swap(cv[4 * q], cv[4 * q + 2], false, false); pw[q].x = r0[0]; pw[q].z = r0[1]; }
;   if constexpr (G == 5 || G == 11 || G == 17 || G == 23) { constexpr int q = (G - 5) / 6; auto r1 = __builtin_amdgcn_permlane32_swap(cv[4 * q + 1], cv[4 * q + 3], false, false); pw[q].y = r1[0]; pw[q].w = r1[1]; }
; }
.Lcv_done:
	v_exp_f32_e32 v1, v249
	v_exp_f32_e32 v101, v84
	v_exp_f32_e32 v103, v85
	v_exp_f32_e32 v205, v89
	v_exp_f32_e32 v206, v90
	v_sub_f32_e32 v102, v70, v140
	v_sub_f32_e32 v204, v74, v140
	v_exp_f32_e32 v160, v88
	v_sub_f32_e32 v88, v69, v140
	v_sub_f32_e32 v158, v72, v140
	v_exp_f32_e32 v154, v86
	v_exp_f32_e32 v159, v87
	v_exp_f32_e32 v208, v91
	v_exp_f32_e32 v209, v92
	v_exp_f32_e32 v210, v93
	v_exp_f32_e32 v211, v94
	v_sub_f32_e32 v155, v71, v140
	v_sub_f32_e32 v161, v73, v140
	v_sub_f32_e32 v207, v75, v140
	ds_read_b128 v[68:71], v178 offset:32768
	ds_read_b128 v[84:87], v178 offset:36864
	s_waitcnt lgkmcnt(0)
	ds_read_b128 v[104:107], v179 offset:32768
	ds_read_b128 v[108:111], v179 offset:36864
	v_mfma_f32_32x32x16_bf16 v[68:83], v[68:71], v[126:129], 0
	v_cvt_pk_bf16_f32 v100, v1, v101
	v_exp_f32_e32 v226, v99
	v_add_f32_e32 v227, 0, v1
	v_exp_f32_e32 v1, v88
	v_mfma_f32_32x32x16_bf16 v[84:99], v[84:87], v[126:129], 0
	v_add_f32_e32 v228, 0, v101
	v_cvt_pk_bf16_f32 v101, v103, v154
	s_waitcnt lgkmcnt(0)
	ds_read_b128 v[130:133], v177 offset:32768
	ds_read_b128 v[150:153], v177 offset:36864
	v_mfma_f32_32x32x16_bf16 v[68:83], v[104:107], v[122:125], v[68:83]
	v_exp_f32_e32 v229, v102
	v_cvt_pk_bf16_f32 v102, v159, v160
	v_add_f32_e32 v230, 0, v103
	v_mfma_f32_32x32x16_bf16 v[84:99], v[108:111], v[122:125], v[84:99]
	v_add_f32_e32 v105, 0, v154
	v_cvt_pk_bf16_f32 v103, v205, v206
	v_exp_f32_e32 v231, v155
	s_waitcnt lgkmcnt(0)
	ds_read_b128 v[106:109], v176 offset:32768
	ds_read_b128 v[154:157], v176 offset:36864
	v_mfma_f32_32x32x16_bf16 v[68:83], v[130:133], v[118:121], v[68:83]
	v_permlane32_swap_b32_e32 v100, v102
	v_exp_f32_e32 v232, v158
	v_add_f32_e32 v227, v159, v227
	v_mfma_f32_32x32x16_bf16 v[84:99], v[150:153], v[118:121], v[84:99]
	v_permlane32_swap_b32_e32 v101, v103
	v_exp_f32_e32 v233, v161
	v_add_f32_e32 v228, v160, v228
	s_waitcnt lgkmcnt(0)
	ds_read_b128 v[130:133], v178 offset:40960
	ds_read_b128 v[150:153], v178 offset:45056
	v_mfma_f32_32x32x16_bf16 v[68:83], v[106:109], v[114:117], v[68:83]
	v_cvt_pk_bf16_f32 v104, v208, v209
	v_exp_f32_e32 v234, v204
	v_add_f32_e32 v230, v205, v230
	v_mfma_f32_32x32x16_bf16 v[84:99], v[154:157], v[114:117], v[84:99]
	v_add_f32_e32 v236, v206, v105
	v_cvt_pk_bf16_f32 v105, v210, v211
	v_exp_f32_e32 v235, v207
	s_waitcnt lgkmcnt(0)
	ds_read_b128 v[108:111], v179 offset:40960
	ds_read_b128 v[154:157], v179 offset:45056
	ds_read_b128 v[204:207], v170
	v_mfma_f32_32x32x16_bf16 v[68:83], v[130:133], v[250:253], v[68:83]
	v_cvt_pk_bf16_f32 v106, v212, v213
	v_exp_f32_e32 v216, v216
	v_add_f32_e32 v227, v208, v227
	v_mfma_f32_32x32x16_bf16 v[84:99], v[150:153], v[250:253], v[84:99]
	v_cvt_pk_bf16_f32 v107, v214, v215
	v_exp_f32_e32 v217, v217
	v_add_f32_e32 v228, v209, v228
	s_waitcnt lgkmcnt(0)
	ds_read_b128 v[130:133], v177 offset:40960
	ds_read_b128 v[150:153], v177 offset:45056
	ds_read_b128 v[158:161], v169
	v_mfma_f32_32x32x16_bf16 v[68:83], v[108:111], v[204:207], v[68:83]
	v_permlane32_swap_b32_e32 v104, v106
	v_exp_f32_e32 v218, v218
	v_add_f32_e32 v230, v210, v230
	v_mfma_f32_32x32x16_bf16 v[84:99], v[154:157], v[204:207], v[84:99]
	v_add_f32_e32 v111, v211, v236
	v_permlane32_swap_b32_e32 v105, v107
	v_exp_f32_e32 v219, v219
	s_waitcnt lgkmcnt(0)
	ds_read_b128 v[154:157], v176 offset:40960
	ds_read_b128 v[204:207], v176 offset:45056
	ds_read_b128 v[208:211], v168
	v_mfma_f32_32x32x16_bf16 v[68:83], v[130:133], v[158:161], v[68:83]
	v_cvt_pk_bf16_f32 v108, v226, v1
	v_exp_f32_e32 v220, v220
	v_add_f32_e32 v212, v212, v227
	v_mfma_f32_32x32x16_bf16 v[84:99], v[150:153], v[158:161], v[84:99]
	v_cvt_pk_bf16_f32 v109, v229, v231
	v_exp_f32_e32 v221, v221
	v_add_f32_e32 v213, v213, v228
	s_waitcnt lgkmcnt(0)
	ds_read_b128 v[130:133], v178 offset:49152
	ds_read_b128 v[150:153], v178 offset:53248
	ds_read_b128 v[158:161], v171 offset:4096
	v_mfma_f32_32x32x16_bf16 v[68:83], v[154:157], v[208:211], v[68:83]
	v_cvt_pk_bf16_f32 v110, v232, v233
	v_exp_f32_e32 v222, v222
	v_add_f32_e32 v214, v214, v230
	v_mfma_f32_32x32x16_bf16 v[84:99], v[204:207], v[208:211], v[84:99]
	v_add_f32_e32 v215, v215, v111
	v_cvt_pk_bf16_f32 v111, v234, v235
	v_exp_f32_e32 v223, v223
	s_waitcnt lgkmcnt(0)
	ds_read_b128 v[154:157], v179 offset:49152
	ds_read_b128 v[204:207], v179 offset:53248
	ds_read_b128 v[208:211], v170 offset:4096
	v_mfma_f32_32x32x16_bf16 v[68:83], v[130:133], v[158:161], v[68:83]
	v_add_f32_e32 v1, v1, v213
	v_permlane32_swap_b32_e32 v108, v110
	v_add_f32_e32 v226, v226, v212
	v_mfma_f32_32x32x16_bf16 v[84:99], v[150:153], v[158:161], v[84:99]
	v_add_f32_e32 v131, v229, v214
	v_add_f32_e32 v132, v231, v215
	v_permlane32_swap_b32_e32 v109, v111
	s_waitcnt lgkmcnt(0)
	ds_read_b128 v[150:153], v177 offset:49152
	ds_read_b128 v[158:161], v177 offset:53248
	ds_read_b128 v[212:215], v169 offset:4096
	v_mfma_f32_32x32x16_bf16 v[68:83], v[154:157], v[208:211], v[68:83]
	v_add_f32_e32 v133, v232, v226
	v_add_f32_e32 v1, v233, v1
	v_cvt_pk_bf16_f32 v130, v216, v217
	v_mfma_f32_32x32x16_bf16 v[84:99], v[204:207], v[208:211], v[84:99]
	v_add_f32_e32 v226, v234, v131
	v_cvt_pk_bf16_f32 v131, v218, v219
	v_add_f32_e32 v227, v235, v132
	s_waitcnt lgkmcnt(0)
	ds_read_b128 v[154:157], v176 offset:49152
	ds_read_b128 v[204:207], v176 offset:53248
	ds_read_b128 v[208:211], v168 offset:4096
	v_mfma_f32_32x32x16_bf16 v[68:83], v[150:153], v[212:215], v[68:83]
	v_add_f32_e32 v1, v217, v1
	v_cvt_pk_bf16_f32 v132, v220, v221
	v_add_f32_e32 v216, v216, v133
	v_mfma_f32_32x32x16_bf16 v[84:99], v[158:161], v[212:215], v[84:99]
	v_cvt_pk_bf16_f32 v133, v222, v223
	v_add_f32_e32 v150, v218, v226
	v_add_f32_e32 v151, v219, v227
	s_waitcnt lgkmcnt(0)
	v_mfma_f32_32x32x16_bf16 v[68:83], v[154:157], v[208:211], v[68:83]
	v_add_f32_e32 v1, v221, v1
	v_permlane32_swap_b32_e32 v130, v132
	v_add_f32_e32 v152, v220, v216
	v_mfma_f32_32x32x16_bf16 v[84:99], v[204:207], v[208:211], v[84:99]
	v_permlane32_swap_b32_e32 v131, v133
	v_add_f32_e32 v150, v222, v150
	v_add_f32_e32 v151, v223, v151
	v_add_f32_e32 v1, v152, v1
	v_add_f32_e32 v150, v150, v151
	v_add_f32_e32 v205, v1, v150
	v_mov_b32_e32 v206, v205
	s_nop 1
	v_permlane32_swap_b32_e32 v205, v206
